# MLA attention: 32-way row max as 17 v_max3_f32 (was 56 ops incl. 32 self-max canonicalisations)
# baseline (speedup 1.0000x reference)
; #define MFMA32(a, b, c) __builtin_amdgcn_mfma_f32_32x32x16_bf16((a), (b), (c), 0, 0, 0)
; #define ATT_LDK(buf, g) do { _Pragma("unroll") for (int kk = 0; kk < 2; ++kk) { \
;                 ka[buf][kk][0] = *(const LAS bf16x8*)(Kb + r * KSTR + (2 * (g) + kk) * 32 + hh * 16); ka[buf][kk][1] = *(const LAS bf16x8*)(Kb + (32 + r) * KSTR + (2 * (g) + kk) * 32 + hh * 16); } } while (0)
; #define ATT_LDV(buf, d) do { _Pragma("unroll") for (int kb = 0; kb < 2; ++kb) _Pragma("unroll") for (int s = 0; s < 2; ++s) { \
;                 const LAS unsigned char* p_ = Vb + vlane + (32 * kb + 16 * s) * VSTR + (d) * 64; vl[buf][2 * kb + s] = trread(p_); vh[buf][2 * kb + s] = trread(p_ + 8 * VSTR); } } while (0)
; template <int NKS, bool ALLIN = false> ...
;     ...
;             f32x16 s0, s1;
; #pragma unroll
;             for (int i = 0; i < 16; ++i) { s0[i] = 0.f; s1[i] = 0.f; }
;             bf16x8 ka[2][2][2];
;     ...
;             ATT_LDK(0, 0); ATT_LDK(1, 1);
;             __builtin_amdgcn_sched_barrier(0);
; #pragma unroll
;             for (int g = 0; g < NKS / 2; ++g) {
; #pragma unroll
;                 for (int kk = 0; kk < 2; ++kk) { s0 = MFMA32(ka[g & 1][kk][0], qf[2 * g + kk], s0); s1 = MFMA32(ka[g & 1][kk][1], qf[2 * g + kk], s1); }
;                 __builtin_amdgcn_sched_barrier(0);
;                 if (g + 2 < NKS / 2) { ATT_LDK(g & 1, g + 2); __builtin_amdgcn_sched_barrier(0); }
;             }
;     ...
;             s16x4 vl[2][4], vh[2][4];
;     ...
;             ATT_LDV(0, 0); ATT_LDV(1, 1);
;             __builtin_amdgcn_sched_barrier(0);
;             float mx = -INFINITY;
; #pragma unroll
;             for (int i = 0; i < 16; ++i) mx = fmaxf(mx, fmaxf(s0[i], s1[i]));
;             mx = fmaxf(mx, __shfl_xor(mx, 32)) * c2;
.LBB0_108:
	s_and_b32 s19, s22, 1
	s_mul_i32 s22, s19, 0x6400
	v_add_u32_e32 v0, s22, v215
	ds_read_b128 v[2:5], v0
	ds_read_b128 v[6:9], v0 offset:32
	ds_read_b128 v[10:13], v0 offset:12800
	ds_read_b128 v[180:183], v0 offset:12832
	ds_read_b128 v[184:187], v0 offset:64
	ds_read_b128 v[188:191], v0 offset:96
	ds_read_b128 v[192:195], v0 offset:12864
	ds_read_b128 v[196:199], v0 offset:12896
	s_mulk_i32 s19, 0x5000
	s_waitcnt lgkmcnt(7)
	v_mfma_f32_32x32x16_bf16 v[96:111], v[2:5], v[132:135], 0
	s_waitcnt lgkmcnt(5)
	v_mfma_f32_32x32x16_bf16 v[80:95], v[10:13], v[132:135], 0
	v_mfma_f32_32x32x16_bf16 v[96:111], v[6:9], v[136:139], v[96:111]
	s_waitcnt lgkmcnt(4)
	v_mfma_f32_32x32x16_bf16 v[80:95], v[180:183], v[136:139], v[80:95]
	ds_read_b128 v[2:5], v0 offset:128
	ds_read_b128 v[6:9], v0 offset:160
	ds_read_b128 v[10:13], v0 offset:12928
	ds_read_b128 v[180:183], v0 offset:12960
	s_waitcnt lgkmcnt(7)
	v_mfma_f32_32x32x16_bf16 v[96:111], v[184:187], v[140:143], v[96:111]
	s_waitcnt lgkmcnt(5)
	v_mfma_f32_32x32x16_bf16 v[80:95], v[192:195], v[140:143], v[80:95]
	v_mfma_f32_32x32x16_bf16 v[96:111], v[188:191], v[144:147], v[96:111]
	s_waitcnt lgkmcnt(4)
	v_mfma_f32_32x32x16_bf16 v[80:95], v[196:199], v[144:147], v[80:95]
	ds_read_b128 v[184:187], v0 offset:192
	ds_read_b128 v[188:191], v0 offset:224
	ds_read_b128 v[192:195], v0 offset:12992
	ds_read_b128 v[196:199], v0 offset:13024
	s_waitcnt lgkmcnt(7)
	v_mfma_f32_32x32x16_bf16 v[96:111], v[2:5], v[148:151], v[96:111]
	s_waitcnt lgkmcnt(5)
	v_mfma_f32_32x32x16_bf16 v[80:95], v[10:13], v[148:151], v[80:95]
	v_mfma_f32_32x32x16_bf16 v[96:111], v[6:9], v[152:155], v[96:111]
	s_waitcnt lgkmcnt(4)
	v_mfma_f32_32x32x16_bf16 v[80:95], v[180:183], v[152:155], v[80:95]
	ds_read_b128 v[2:5], v0 offset:256
	ds_read_b128 v[6:9], v0 offset:288
	ds_read_b128 v[10:13], v0 offset:13056
	ds_read_b128 v[180:183], v0 offset:13088
	s_waitcnt lgkmcnt(7)
	v_mfma_f32_32x32x16_bf16 v[96:111], v[184:187], v[156:159], v[96:111]
	s_waitcnt lgkmcnt(5)
	v_mfma_f32_32x32x16_bf16 v[80:95], v[192:195], v[156:159], v[80:95]
	v_mfma_f32_32x32x16_bf16 v[96:111], v[188:191], v[160:163], v[96:111]
	s_waitcnt lgkmcnt(4)
	v_mfma_f32_32x32x16_bf16 v[80:95], v[196:199], v[160:163], v[80:95]
	ds_read_b128 v[184:187], v0 offset:320
	ds_read_b128 v[188:191], v0 offset:352
	ds_read_b128 v[192:195], v0 offset:13120
	ds_read_b128 v[196:199], v0 offset:13152
	s_waitcnt lgkmcnt(7)
	v_mfma_f32_32x32x16_bf16 v[96:111], v[2:5], v[164:167], v[96:111]
	s_waitcnt lgkmcnt(5)
	v_mfma_f32_32x32x16_bf16 v[80:95], v[10:13], v[164:167], v[80:95]
	v_mfma_f32_32x32x16_bf16 v[96:111], v[6:9], v[168:171], v[96:111]
	s_waitcnt lgkmcnt(4)
	v_mfma_f32_32x32x16_bf16 v[80:95], v[180:183], v[168:171], v[80:95]
	s_waitcnt lgkmcnt(3)
	v_mfma_f32_32x32x16_bf16 v[96:111], v[184:187], v[172:175], v[96:111]
	s_waitcnt lgkmcnt(1)
	v_mfma_f32_32x32x16_bf16 v[80:95], v[192:195], v[172:175], v[80:95]
	v_mfma_f32_32x32x16_bf16 v[96:111], v[188:191], v[176:179], v[96:111]
	s_waitcnt lgkmcnt(0)
	v_mfma_f32_32x32x16_bf16 v[80:95], v[196:199], v[176:179], v[80:95]
	v_add_u32_e32 v222, s19, v213
	v_add_u32_e32 v218, 0xc800, v222
	ds_read_b64_tr_b16 v[184:185], v222 offset:51200
	ds_read_b64_tr_b16 v[186:187], v222 offset:53760
	ds_read_b64_tr_b16 v[182:183], v222 offset:53824
	ds_read_b64_tr_b16 v[180:181], v222 offset:51264
	ds_read_b64_tr_b16 v[196:197], v222 offset:56320
	ds_read_b64_tr_b16 v[198:199], v222 offset:58880
	ds_read_b64_tr_b16 v[12:13], v222 offset:58944
	ds_read_b64_tr_b16 v[10:11], v222 offset:56384
	ds_read_b64_tr_b16 v[192:193], v222 offset:61440
	ds_read_b64_tr_b16 v[194:195], v222 offset:64000
	ds_read_b64_tr_b16 v[8:9], v222 offset:64064
	ds_read_b64_tr_b16 v[6:7], v222 offset:61504
	ds_read_b64_tr_b16 v[188:189], v218 offset:15360
	ds_read_b64_tr_b16 v[190:191], v218 offset:17920
	ds_read_b64_tr_b16 v[4:5], v218 offset:17984
	ds_read_b64_tr_b16 v[2:3], v218 offset:15424
	v_max3_f32 v0, v80, v96, s73
	v_max3_f32 v14, v81, v97, s73
	v_max3_f32 v0, v0, v82, v98
	v_max3_f32 v14, v14, v83, v99
	v_max3_f32 v0, v0, v84, v100
	v_max3_f32 v14, v14, v85, v101
	v_max3_f32 v0, v0, v86, v102
	v_max3_f32 v14, v14, v87, v103
	v_max3_f32 v0, v0, v88, v104
	v_max3_f32 v14, v14, v89, v105
	v_max3_f32 v0, v0, v90, v106
	v_max3_f32 v14, v14, v91, v107
	v_max3_f32 v0, v0, v92, v108
	v_max3_f32 v14, v14, v93, v109
	v_max3_f32 v0, v0, v94, v110
	v_max3_f32 v14, v14, v95, v111
	v_max_f32_e32 v0, v0, v14
	v_and_b32_e32 v15, 64, v220
	v_xor_b32_e32 v14, 32, v220
	v_add_u32_e32 v15, 64, v15
	v_cmp_lt_i32_e32 vcc, v14, v15
	s_nop 1
	v_cndmask_b32_e32 v14, v220, v14, vcc
	v_lshlrev_b32_e32 v14, 2, v14
	ds_bpermute_b32 v14, v14, v0
	s_waitcnt lgkmcnt(0)
; #define MFMA32(a, b, c) __builtin_amdgcn_mfma_f32_32x32x16_bf16((a), (b), (c), 0, 0, 0)
; __device__ __forceinline__ bf16x8 cat44(s16x4 lo, s16x4 hi) { return (bf16x8){lo[0], lo[1], lo[2], lo[3], hi[0], hi[1], hi[2], hi[3]}; }
; #define ATT_LDV(buf, d) do { _Pragma("unroll") for (int kb = 0; kb < 2; ++kb) _Pragma("unroll") for (int s = 0; s < 2; ++s) { \
;                 const LAS unsigned char* p_ = Vb + vlane + (32 * kb + 16 * s) * VSTR + (d) * 64; vl[buf][2 * kb + s] = trread(p_); vh[buf][2 * kb + s] = trread(p_ + 8 * VSTR); } } while (0)
; template <int NKS, bool ALLIN = false> ...
;     ...
;             float mx = -INFINITY;
; #pragma unroll
;             for (int i = 0; i < 16; ++i) mx = fmaxf(mx, fmaxf(s0[i], s1[i]));
;             mx = fmaxf(mx, __shfl_xor(mx, 32)) * c2;
;             const float mnew = fmaxf(mrun, mx), alpha = __builtin_amdgcn_exp2f(mrun - mnew); mrun = mnew;
;             float ls = 0.f;
; #pragma unroll
;             for (int i = 0; i < 16; ++i) { s0[i] = __builtin_amdgcn_exp2f(fmaf(s0[i], c2, -mnew)); s1[i] = __builtin_amdgcn_exp2f(fmaf(s1[i], c2, -mnew)); ls += s0[i] + s1[i]; }
;             lrun = lrun * alpha + ls;
; #pragma unroll
;             for (int d = 0; d < 4; ++d)
; #pragma unroll
;                 for (int i = 0; i < 16; ++i) o[d][i] *= alpha;
;             bf16x8 pf[4];
;             pf[0] = packacc8(s0, 0); pf[1] = packacc8(s0, 8); pf[2] = packacc8(s1, 0); pf[3] = packacc8(s1, 8);
;             __builtin_amdgcn_sched_barrier(0);
; #pragma unroll
;             for (int d = 0; d < 4; ++d) {
; #pragma unroll
;                 for (int j = 0; j < 4; ++j) o[d] = MFMA32(cat44(vl[d & 1][j], vh[d & 1][j]), pf[j], o[d]);
;                 __builtin_amdgcn_sched_barrier(0);
;                 if (d + 2 < 4) { ATT_LDV(d & 1, d + 2); __builtin_amdgcn_sched_barrier(0); }
	v_max_f32_e32 v14, v14, v14
	v_max_f32_e32 v0, v0, v14
	v_mul_f32_e32 v0, 0x3dd53b94, v0
	v_max_f32_e32 v14, v219, v219
	v_max_f32_e32 v223, v14, v0
	v_fma_f32 v14, v98, s80, -v223
	v_exp_f32_e32 v234, v14
	v_fma_f32 v14, v82, s80, -v223
	v_fma_f32 v0, v96, s80, -v223
	v_exp_f32_e32 v235, v14
	v_fma_f32 v14, v99, s80, -v223
	v_exp_f32_e32 v224, v0
	v_fma_f32 v0, v80, s80, -v223
	v_exp_f32_e32 v236, v14
	v_fma_f32 v14, v83, s80, -v223
	v_exp_f32_e32 v225, v0
	v_fma_f32 v0, v97, s80, -v223
	v_exp_f32_e32 v237, v14
	v_fma_f32 v14, v100, s80, -v223
	v_exp_f32_e32 v226, v0
	v_fma_f32 v0, v81, s80, -v223
	v_exp_f32_e32 v81, v14
	v_fma_f32 v14, v84, s80, -v223
	v_exp_f32_e32 v15, v14
	v_fma_f32 v14, v101, s80, -v223
	v_fma_f32 v82, v102, s80, -v223
	v_exp_f32_e32 v80, v14
	v_fma_f32 v14, v85, s80, -v223
	v_exp_f32_e32 v85, v82
	v_fma_f32 v82, v86, s80, -v223
	v_fma_f32 v86, v104, s80, -v223
	v_exp_f32_e32 v101, v86
	v_fma_f32 v86, v88, s80, -v223
	v_fma_f32 v88, v106, s80, -v223
	v_exp_f32_e32 v83, v82
	v_fma_f32 v82, v103, s80, -v223
	v_exp_f32_e32 v103, v88
	v_fma_f32 v88, v90, s80, -v223
	v_exp_f32_e32 v84, v82
	v_fma_f32 v82, v87, s80, -v223
	v_exp_f32_e32 v87, v86
	v_fma_f32 v86, v105, s80, -v223
	v_exp_f32_e32 v105, v88
	v_fma_f32 v88, v107, s80, -v223
	v_exp_f32_e32 v102, v88
	v_fma_f32 v88, v91, s80, -v223
	v_exp_f32_e32 v227, v0
	v_exp_f32_e32 v104, v88
	v_fma_f32 v88, v108, s80, -v223
	v_exp_f32_e32 v107, v88
	v_fma_f32 v88, v92, s80, -v223
	v_exp_f32_e32 v231, v88
	v_fma_f32 v88, v109, s80, -v223
	v_sub_f32_e32 v0, v219, v223
	v_add_f32_e32 v219, v224, v225
	v_exp_f32_e32 v14, v14
	v_exp_f32_e32 v106, v88
	v_fma_f32 v88, v93, s80, -v223
	v_add_f32_e32 v229, v226, v227
	v_exp_f32_e32 v230, v88
	v_fma_f32 v88, v110, s80, -v223
	v_add_f32_e32 v110, 0, v219
	v_exp_f32_e32 v82, v82
	v_add_f32_e32 v238, v234, v235
	v_add_f32_e32 v110, v229, v110
	v_add_f32_e32 v239, v236, v237
	v_exp_f32_e32 v100, v86
	v_fma_f32 v86, v89, s80, -v223
	v_add_f32_e32 v110, v238, v110
	v_pk_add_f32 v[96:97], v[80:81], v[14:15]
	v_exp_f32_e32 v86, v86
	v_add_f32_e32 v110, v239, v110
	v_exp_f32_e32 v109, v88
	v_fma_f32 v88, v94, s80, -v223
	v_add_f32_e32 v97, v97, v110
	v_pk_add_f32 v[98:99], v[84:85], v[82:83]
	v_exp_f32_e32 v233, v88
	v_fma_f32 v88, v111, s80, -v223
	v_add_f32_e32 v96, v96, v97
	v_exp_f32_e32 v108, v88
	v_fma_f32 v88, v95, s80, -v223
	v_add_f32_e32 v96, v99, v96
	v_exp_f32_e32 v232, v88
	v_pk_add_f32 v[88:89], v[100:101], v[86:87]
	v_add_f32_e32 v96, v98, v96
	v_add_f32_e32 v89, v89, v96
	v_pk_add_f32 v[90:91], v[102:103], v[104:105]
	v_add_f32_e32 v88, v88, v89
	v_add_f32_e32 v88, v91, v88
	v_exp_f32_e32 v0, v0
	v_pk_add_f32 v[92:93], v[106:107], v[230:231]
	v_add_f32_e32 v88, v90, v88
	v_add_f32_e32 v88, v93, v88
	v_pk_add_f32 v[94:95], v[108:109], v[232:233]
	v_add_f32_e32 v88, v92, v88
	v_add_f32_e32 v88, v95, v88
	v_pk_mul_f32 v[78:79], v[78:79], v[0:1] op_sel_hi:[1,0]
	v_pk_mul_f32 v[76:77], v[76:77], v[0:1] op_sel_hi:[1,0]
	v_pk_mul_f32 v[74:75], v[74:75], v[0:1] op_sel_hi:[1,0]
	v_pk_mul_f32 v[72:73], v[72:73], v[0:1] op_sel_hi:[1,0]
	v_pk_mul_f32 v[70:71], v[70:71], v[0:1] op_sel_hi:[1,0]
	v_pk_mul_f32 v[68:69], v[68:69], v[0:1] op_sel_hi:[1,0]
	v_pk_mul_f32 v[66:67], v[66:67], v[0:1] op_sel_hi:[1,0]
	v_pk_mul_f32 v[64:65], v[64:65], v[0:1] op_sel_hi:[1,0]
	v_pk_mul_f32 v[62:63], v[62:63], v[0:1] op_sel_hi:[1,0]
	v_pk_mul_f32 v[60:61], v[60:61], v[0:1] op_sel_hi:[1,0]
	v_pk_mul_f32 v[58:59], v[58:59], v[0:1] op_sel_hi:[1,0]
	v_pk_mul_f32 v[56:57], v[56:57], v[0:1] op_sel_hi:[1,0]
	v_pk_mul_f32 v[54:55], v[54:55], v[0:1] op_sel_hi:[1,0]
	v_pk_mul_f32 v[52:53], v[52:53], v[0:1] op_sel_hi:[1,0]
	v_pk_mul_f32 v[50:51], v[50:51], v[0:1] op_sel_hi:[1,0]
	v_pk_mul_f32 v[48:49], v[48:49], v[0:1] op_sel_hi:[1,0]
	v_pk_mul_f32 v[46:47], v[46:47], v[0:1] op_sel_hi:[1,0]
	v_pk_mul_f32 v[44:45], v[44:45], v[0:1] op_sel_hi:[1,0]
	v_pk_mul_f32 v[42:43], v[42:43], v[0:1] op_sel_hi:[1,0]
	v_pk_mul_f32 v[40:41], v[40:41], v[0:1] op_sel_hi:[1,0]
	v_pk_mul_f32 v[38:39], v[38:39], v[0:1] op_sel_hi:[1,0]
	v_pk_mul_f32 v[36:37], v[36:37], v[0:1] op_sel_hi:[1,0]
	v_pk_mul_f32 v[34:35], v[34:35], v[0:1] op_sel_hi:[1,0]
	v_pk_mul_f32 v[32:33], v[32:33], v[0:1] op_sel_hi:[1,0]
	v_pk_mul_f32 v[30:31], v[30:31], v[0:1] op_sel_hi:[1,0]
	v_pk_mul_f32 v[28:29], v[28:29], v[0:1] op_sel_hi:[1,0]
	v_pk_mul_f32 v[26:27], v[26:27], v[0:1] op_sel_hi:[1,0]
	v_pk_mul_f32 v[24:25], v[24:25], v[0:1] op_sel_hi:[1,0]
	v_pk_mul_f32 v[22:23], v[22:23], v[0:1] op_sel_hi:[1,0]
	v_pk_mul_f32 v[20:21], v[20:21], v[0:1] op_sel_hi:[1,0]
	v_pk_mul_f32 v[18:19], v[18:19], v[0:1] op_sel_hi:[1,0]
	v_pk_mul_f32 v[16:17], v[16:17], v[0:1] op_sel_hi:[1,0]
	v_add_f32_e32 v219, v94, v88
	v_cvt_pk_bf16_f32 v88, v224, v226
	v_cvt_pk_bf16_f32 v89, v234, v236
	v_cvt_pk_bf16_f32 v90, v81, v80
	v_cvt_pk_bf16_f32 v91, v85, v84
	v_cvt_pk_bf16_f32 v92, v101, v100
	v_cvt_pk_bf16_f32 v93, v103, v102
	v_cvt_pk_bf16_f32 v94, v107, v106
	v_cvt_pk_bf16_f32 v95, v109, v108
	v_cvt_pk_bf16_f32 v96, v225, v227
	v_cvt_pk_bf16_f32 v97, v235, v237
	v_cvt_pk_bf16_f32 v98, v15, v14
	v_cvt_pk_bf16_f32 v99, v83, v82
	v_cvt_pk_bf16_f32 v80, v87, v86
	v_cvt_pk_bf16_f32 v81, v105, v104
	v_cvt_pk_bf16_f32 v82, v231, v230
	v_cvt_pk_bf16_f32 v83, v233, v232
	s_nop 0
	v_mfma_f32_32x32x16_bf16 v[64:79], v[184:187], v[88:91], v[64:79]
	v_mfma_f32_32x32x16_bf16 v[64:79], v[196:199], v[92:95], v[64:79]
	v_mfma_f32_32x32x16_bf16 v[64:79], v[192:195], v[96:99], v[64:79]
	v_mfma_f32_32x32x16_bf16 v[64:79], v[188:191], v[80:83], v[64:79]
	ds_read_b64_tr_b16 v[84:85], v222 offset:51328
	ds_read_b64_tr_b16 v[86:87], v222 offset:53888
	ds_read_b64_tr_b16 v[100:101], v222 offset:56448
	ds_read_b64_tr_b16 v[102:103], v222 offset:59008
	ds_read_b64_tr_b16 v[104:105], v222 offset:61568
	ds_read_b64_tr_b16 v[106:107], v222 offset:64128
	ds_read_b64_tr_b16 v[108:109], v218 offset:15488
	ds_read_b64_tr_b16 v[110:111], v218 offset:18048
	v_mfma_f32_32x32x16_bf16 v[48:63], v[180:183], v[88:91], v[48:63]
	v_mfma_f32_32x32x16_bf16 v[48:63], v[10:13], v[92:95], v[48:63]
	v_mfma_f32_32x32x16_bf16 v[48:63], v[6:9], v[96:99], v[48:63]
	v_mfma_f32_32x32x16_bf16 v[48:63], v[2:5], v[80:83], v[48:63]
	ds_read_b64_tr_b16 v[2:3], v222 offset:51392
	ds_read_b64_tr_b16 v[4:5], v222 offset:53952
	ds_read_b64_tr_b16 v[6:7], v222 offset:56512
	ds_read_b64_tr_b16 v[8:9], v222 offset:59072
	ds_read_b64_tr_b16 v[10:11], v222 offset:61632
	ds_read_b64_tr_b16 v[12:13], v222 offset:64192
	ds_read_b64_tr_b16 v[180:181], v218 offset:15552
	ds_read_b64_tr_b16 v[182:183], v218 offset:18112
	s_waitcnt lgkmcnt(14)
; #define MFMA32(a, b, c) __builtin_amdgcn_mfma_f32_32x32x16_bf16((a), (b), (c), 0, 0, 0)
; __device__ __forceinline__ bf16x8 cat44(s16x4 lo, s16x4 hi) { return (bf16x8){lo[0], lo[1], lo[2], lo[3], hi[0], hi[1], hi[2], hi[3]}; }
; #define ATT_LDV(buf, d) do { _Pragma("unroll") for (int kb = 0; kb < 2; ++kb) _Pragma("unroll") for (int s = 0; s < 2; ++s) { \
;                 const LAS unsigned char* p_ = Vb + vlane + (32 * kb + 16 * s) * VSTR + (d) * 64; vl[buf][2 * kb + s] = trread(p_); vh[buf][2 * kb + s] = trread(p_ + 8 * VSTR); } } while (0)
; template <int NKS, bool ALLIN = false> ...
;     ...
;             lrun = lrun * alpha + ls;
; #pragma unroll
;             for (int d = 0; d < 4; ++d)
; #pragma unroll
;                 for (int i = 0; i < 16; ++i) o[d][i] *= alpha;
;             bf16x8 pf[4];
;             pf[0] = packacc8(s0, 0); pf[1] = packacc8(s0, 8); pf[2] = packacc8(s1, 0); pf[3] = packacc8(s1, 8);
;             __builtin_amdgcn_sched_barrier(0);
; #pragma unroll
;             for (int d = 0; d < 4; ++d) {
; #pragma unroll
;                 for (int j = 0; j < 4; ++j) o[d] = MFMA32(cat44(vl[d & 1][j], vh[d & 1][j]), pf[j], o[d]);
;                 __builtin_amdgcn_sched_barrier(0);
;                 if (d + 2 < 4) { ATT_LDV(d & 1, d + 2); __builtin_amdgcn_sched_barrier(0); }
;             }
	v_mfma_f32_32x32x16_bf16 v[32:47], v[84:87], v[88:91], v[32:47]
	s_waitcnt lgkmcnt(12)
	v_mfma_f32_32x32x16_bf16 v[32:47], v[100:103], v[92:95], v[32:47]
	s_waitcnt lgkmcnt(10)
	v_mfma_f32_32x32x16_bf16 v[32:47], v[104:107], v[96:99], v[32:47]
	s_waitcnt lgkmcnt(8)
	v_mfma_f32_32x32x16_bf16 v[32:47], v[108:111], v[80:83], v[32:47]
	s_waitcnt lgkmcnt(6)
	v_mfma_f32_32x32x16_bf16 v[16:31], v[2:5], v[88:91], v[16:31]
	s_waitcnt lgkmcnt(4)
	v_mfma_f32_32x32x16_bf16 v[16:31], v[6:9], v[92:95], v[16:31]
	s_waitcnt lgkmcnt(2)
	v_mfma_f32_32x32x16_bf16 v[16:31], v[10:13], v[96:99], v[16:31]
	s_waitcnt lgkmcnt(0)
	v_mfma_f32_32x32x16_bf16 v[16:31], v[180:183], v[80:83], v[16:31]
	v_fmac_f32_e32 v219, v214, v0
	v_mov_b32_e32 v214, v219
	v_mov_b32_e32 v219, v223
	s_andn2_b64 vcc, exec, s[16:17]
	s_cbranch_vccz .LBB0_104
	s_branch .LBB0_105
	s_nop 0
	s_nop 0
	s_nop 0
	s_nop 0
	s_nop 0
	s_nop 0
	s_nop 0
	s_nop 0
	s_nop 0
	s_nop 0
	s_nop 0
	s_nop 0
	s_nop 0
	s_nop 0
	s_nop 0
	s_nop 0
	s_nop 0
	s_nop 0
	s_nop 0
	s_nop 0
	s_nop 0
	s_nop 0
	s_nop 0
	s_nop 0
	s_nop 0
	s_nop 0
	s_nop 0
	s_nop 0
	s_nop 0
	s_nop 0
	s_nop 0
	s_nop 0
	s_nop 0
	s_nop 0
	s_nop 0
	s_nop 0
